# prompt-group attention item: query-fragment loads issued at the top of the item (registers chosen among those the item itself defines later, so no value that lives across the item is touched)
# baseline (speedup 1.0000x reference)
.LBB0_1210:
	v_mov_b32_e32 v164, v0
	s_sub_i32 s0, s14, s13
	v_ashrrev_i32_e32 v66, 5, v164
	v_lshlrev_b32_e32 v2, 2, v164
	v_ashrrev_i32_e32 v67, 31, v66
	v_and_b32_e32 v98, 0x7c, v2
	v_lshlrev_b64 v[2:3], 11, v[66:67]
	v_add_u32_e32 v67, 0x200, v164
	v_ashrrev_i32_e32 v68, 5, v67
	v_ashrrev_i32_e32 v69, 31, v68
	v_lshlrev_b64 v[4:5], 11, v[68:69]
	v_add_u32_e32 v69, 0x400, v164
	v_ashrrev_i32_e32 v70, 5, v69
	s_addk_i32 s0, 0xff60
	v_ashrrev_i32_e32 v71, 31, v70
	s_ashr_i32 s4, s0, 5
	v_lshlrev_b64 v[10:11], 11, v[70:71]
	v_add_u32_e32 v71, 0x600, v164
	s_ashr_i32 s5, s4, 31
	s_lshl_b32 s6, s14, 8
	v_ashrrev_i32_e32 v72, 5, v71
	s_lshl_b64 s[0:1], s[4:5], 11
	s_and_b32 s6, s6, 0x700
	v_ashrrev_i32_e32 v73, 31, v72
	s_or_b32 s0, s0, s6
	s_lshl_b32 s6, s14, 4
	v_lshlrev_b64 v[12:13], 11, v[72:73]
	v_add_u32_e32 v73, 0x800, v164
	s_and_b32 s7, s6, 0x180
	s_lshl_b64 s[4:5], s[4:5], 19
	v_ashrrev_i32_e32 v74, 5, v73
	s_add_u32 s6, s52, s4
	v_ashrrev_i32_e32 v75, 31, v74
	s_addc_u32 s15, s53, s5
	s_lshl_b32 s16, s7, 2
	v_lshlrev_b64 v[18:19], 11, v[74:75]
	v_add_u32_e32 v75, 0xa00, v164
	s_add_u32 s14, s6, s16
	v_ashrrev_i32_e32 v76, 5, v75
	s_addc_u32 s15, s15, 0
	v_lshlrev_b32_e32 v162, 2, v98
	v_ashrrev_i32_e32 v77, 31, v76
	v_lshl_add_u64 v[62:63], s[14:15], 0, v[162:163]
	v_lshlrev_b64 v[20:21], 11, v[76:77]
	v_add_u32_e32 v77, 0xc00, v164
	v_lshl_add_u64 v[2:3], v[62:63], 0, v[2:3]
	v_lshl_add_u64 v[6:7], v[62:63], 0, v[4:5]
	v_ashrrev_i32_e32 v78, 5, v77
	s_lshl_b64 s[14:15], s[0:1], 10
	s_add_u32 s14, s41, s14
	s_addc_u32 s15, s42, s15
	s_add_u32 s14, s14, s7
	s_addc_u32 s15, s15, 0
	s_add_u32 s14, s14, s7
	s_addc_u32 s15, s15, 0
	v_lshrrev_b32_e32 v104, 6, v164
	v_and_b32_e32 v105, 31, v164
	v_lshl_or_b32 v104, v104, 5, v105
	v_bfe_u32 v105, v164, 5, 1
	v_lshlrev_b32_e32 v104, 10, v104
	v_lshl_add_u32 v104, v105, 4, v104
	global_load_dwordx4 v[100:103], v104, s[14:15]
	global_load_dwordx4 v[154:157], v104, s[14:15] offset:32
	global_load_dwordx4 v[150:153], v104, s[14:15] offset:64
	global_load_dwordx4 v[146:149], v104, s[14:15] offset:96
	global_load_dwordx4 v[142:145], v104, s[14:15] offset:128
	global_load_dwordx4 v[138:141], v104, s[14:15] offset:160
	global_load_dwordx4 v[134:137], v104, s[14:15] offset:192
	global_load_dwordx4 v[130:133], v104, s[14:15] offset:224
	s_barrier
	global_load_dwordx4 v[2:5], v[2:3], off
	s_nop 0
	global_load_dwordx4 v[6:9], v[6:7], off
	v_ashrrev_i32_e32 v79, 31, v78
	v_lshl_add_u64 v[10:11], v[62:63], 0, v[10:11]
	v_lshl_add_u64 v[14:15], v[62:63], 0, v[12:13]
	v_lshlrev_b64 v[26:27], 11, v[78:79]
	v_add_u32_e32 v79, 0xe00, v164
	global_load_dwordx4 v[10:13], v[10:11], off
	s_nop 0
	global_load_dwordx4 v[14:17], v[14:15], off
	v_ashrrev_i32_e32 v80, 5, v79
	v_lshl_add_u64 v[18:19], v[62:63], 0, v[18:19]
	v_lshl_add_u64 v[22:23], v[62:63], 0, v[20:21]
	v_ashrrev_i32_e32 v81, 31, v80
	v_add_u32_e32 v34, 0x1000, v164
	v_add_u32_e32 v36, 0x1200, v164
	global_load_dwordx4 v[18:21], v[18:19], off
	s_nop 0
	global_load_dwordx4 v[22:25], v[22:23], off
	v_lshlrev_b64 v[28:29], 11, v[80:81]
	v_ashrrev_i32_e32 v82, 5, v34
	v_ashrrev_i32_e32 v84, 5, v36
	v_lshl_add_u64 v[26:27], v[62:63], 0, v[26:27]
	s_waitcnt vmcnt(30)
	v_lshl_add_u64 v[30:31], v[62:63], 0, v[28:29]
	v_ashrrev_i32_e32 v83, 31, v82
	v_ashrrev_i32_e32 v85, 31, v84
	s_waitcnt vmcnt(28)
	v_add_u32_e32 v42, 0x1400, v164
	s_waitcnt vmcnt(22)
	v_add_u32_e32 v44, 0x1600, v164
	global_load_dwordx4 v[26:29], v[26:27], off
	s_nop 0
	global_load_dwordx4 v[30:33], v[30:31], off
	v_lshlrev_b64 v[34:35], 11, v[82:83]
	v_lshlrev_b64 v[36:37], 11, v[84:85]
	v_ashrrev_i32_e32 v86, 5, v42
	v_ashrrev_i32_e32 v88, 5, v44
	s_waitcnt vmcnt(22)
	v_add_u32_e32 v50, 0x1800, v164
	v_lshl_add_u64 v[34:35], v[62:63], 0, v[34:35]
	v_lshl_add_u64 v[38:39], v[62:63], 0, v[36:37]
	v_ashrrev_i32_e32 v87, 31, v86
	v_ashrrev_i32_e32 v89, 31, v88
	v_ashrrev_i32_e32 v90, 5, v50
	v_add_u32_e32 v54, 0x1a00, v164
	global_load_dwordx4 v[34:37], v[34:35], off
	s_nop 0
	global_load_dwordx4 v[38:41], v[38:39], off
	v_lshlrev_b64 v[42:43], 11, v[86:87]
	s_waitcnt vmcnt(23)
	v_lshlrev_b64 v[44:45], 11, v[88:89]
	v_ashrrev_i32_e32 v91, 31, v90
	v_ashrrev_i32_e32 v92, 5, v54
	v_add_u32_e32 v58, 0x1c00, v164
	v_lshl_add_u64 v[42:43], v[62:63], 0, v[42:43]
	s_waitcnt vmcnt(20)
	v_lshl_add_u64 v[46:47], v[62:63], 0, v[44:45]
	v_lshlrev_b64 v[50:51], 11, v[90:91]
	v_ashrrev_i32_e32 v93, 31, v92
	v_ashrrev_i32_e32 v94, 5, v58
	v_add_u32_e32 v64, 0x1e00, v164
	global_load_dwordx4 v[42:45], v[42:43], off
	s_nop 0
	global_load_dwordx4 v[46:49], v[46:47], off
	v_lshl_add_u64 v[50:51], v[62:63], 0, v[50:51]
	v_lshlrev_b64 v[54:55], 11, v[92:93]
	v_ashrrev_i32_e32 v95, 31, v94
	v_ashrrev_i32_e32 v96, 5, v64
	global_load_dwordx4 v[50:53], v[50:51], off
	v_lshl_add_u64 v[54:55], v[62:63], 0, v[54:55]
	v_lshlrev_b64 v[58:59], 11, v[94:95]
	v_ashrrev_i32_e32 v97, 31, v96
	global_load_dwordx4 v[54:57], v[54:55], off
	v_lshl_add_u64 v[58:59], v[62:63], 0, v[58:59]
	v_lshlrev_b64 v[64:65], 11, v[96:97]
	global_load_dwordx4 v[58:61], v[58:59], off
	v_lshl_add_u64 v[62:63], v[62:63], 0, v[64:65]
	global_load_dwordx4 v[62:65], v[62:63], off
	s_add_u32 s4, s72, s4
	s_addc_u32 s5, s73, s5
	v_lshl_add_u32 v98, v98, 1, 0
	s_add_u32 s4, s4, s16
	s_addc_u32 s5, s5, 0
	v_ashrrev_i32_e32 v67, 4, v67
	v_and_b32_e32 v160, 31, v164
	v_readfirstlane_b32 s15, v0
	s_lshr_b32 s14, s15, 6
	s_lshl_b32 s6, s14, 5
	v_bfe_u32 v161, v164, 5, 1
	s_cmpk_lt_u32 s15, 0x200
	v_lshlrev_b32_e32 v158, 4, v161
	s_waitcnt vmcnt(15)
	v_cvt_pk_bf16_f32 v2, v2, v3
	v_cvt_pk_bf16_f32 v3, v4, v5
	v_mad_u64_u32 v[4:5], s[16:17], v66, s74, v[98:99]
	ds_write_b64 v4, v[2:3]
	s_waitcnt vmcnt(14)
	v_cvt_pk_bf16_f32 v2, v6, v7
	v_cvt_pk_bf16_f32 v3, v8, v9
	v_mad_u64_u32 v[4:5], s[16:17], v68, s74, v[98:99]
	ds_write_b64 v4, v[2:3]
	s_waitcnt vmcnt(13)
	v_cvt_pk_bf16_f32 v2, v10, v11
	v_cvt_pk_bf16_f32 v3, v12, v13
	v_mad_u64_u32 v[4:5], s[16:17], v70, s74, v[98:99]
	ds_write_b64 v4, v[2:3]
	s_waitcnt vmcnt(12)
	v_cvt_pk_bf16_f32 v2, v14, v15
	v_cvt_pk_bf16_f32 v3, v16, v17
	v_mad_u64_u32 v[4:5], s[16:17], v72, s74, v[98:99]
	ds_write_b64 v4, v[2:3]
	s_waitcnt vmcnt(11)
	v_cvt_pk_bf16_f32 v2, v18, v19
	v_cvt_pk_bf16_f32 v3, v20, v21
	v_mad_u64_u32 v[4:5], s[16:17], v74, s74, v[98:99]
	ds_write_b64 v4, v[2:3]
	s_waitcnt vmcnt(10)
	v_cvt_pk_bf16_f32 v2, v22, v23
	v_cvt_pk_bf16_f32 v3, v24, v25
	v_mad_u64_u32 v[4:5], s[16:17], v76, s74, v[98:99]
	ds_write_b64 v4, v[2:3]
	s_waitcnt vmcnt(9)
	v_cvt_pk_bf16_f32 v2, v26, v27
	v_cvt_pk_bf16_f32 v3, v28, v29
	v_mad_u64_u32 v[4:5], s[16:17], v78, s74, v[98:99]
	ds_write_b64 v4, v[2:3]
	s_waitcnt vmcnt(8)
	v_cvt_pk_bf16_f32 v2, v30, v31
	v_cvt_pk_bf16_f32 v3, v32, v33
	v_mad_u64_u32 v[4:5], s[16:17], v80, s74, v[98:99]
	ds_write_b64 v4, v[2:3]
	s_waitcnt vmcnt(7)
	v_cvt_pk_bf16_f32 v2, v34, v35
	v_cvt_pk_bf16_f32 v3, v36, v37
	v_mad_u64_u32 v[4:5], s[16:17], v82, s74, v[98:99]
	ds_write_b64 v4, v[2:3]
	s_waitcnt vmcnt(6)
	v_cvt_pk_bf16_f32 v2, v38, v39
	v_cvt_pk_bf16_f32 v3, v40, v41
	v_mad_u64_u32 v[4:5], s[16:17], v84, s74, v[98:99]
	ds_write_b64 v4, v[2:3]
	s_waitcnt vmcnt(5)
	v_cvt_pk_bf16_f32 v2, v42, v43
	v_cvt_pk_bf16_f32 v3, v44, v45
	v_mad_u64_u32 v[4:5], s[16:17], v86, s74, v[98:99]
	ds_write_b64 v4, v[2:3]
	s_waitcnt vmcnt(4)
	v_cvt_pk_bf16_f32 v2, v46, v47
	v_cvt_pk_bf16_f32 v3, v48, v49
	v_mad_u64_u32 v[4:5], s[16:17], v88, s74, v[98:99]
	ds_write_b64 v4, v[2:3]
	s_waitcnt vmcnt(3)
	v_cvt_pk_bf16_f32 v2, v50, v51
	v_cvt_pk_bf16_f32 v3, v52, v53
	v_mad_u64_u32 v[4:5], s[16:17], v90, s74, v[98:99]
	ds_write_b64 v4, v[2:3]
	s_waitcnt vmcnt(2)
	v_cvt_pk_bf16_f32 v2, v54, v55
	v_cvt_pk_bf16_f32 v3, v56, v57
	v_mad_u64_u32 v[4:5], s[16:17], v92, s74, v[98:99]
	ds_write_b64 v4, v[2:3]
	s_waitcnt vmcnt(1)
	v_cvt_pk_bf16_f32 v2, v58, v59
	v_cvt_pk_bf16_f32 v3, v60, v61
	v_mad_u64_u32 v[4:5], s[16:17], v94, s74, v[98:99]
	ds_write_b64 v4, v[2:3]
	s_waitcnt vmcnt(0)
	v_cvt_pk_bf16_f32 v2, v62, v63
	v_cvt_pk_bf16_f32 v3, v64, v65
	v_mad_u64_u32 v[4:5], s[16:17], v96, s74, v[98:99]
	v_ashrrev_i32_e32 v66, 4, v164
	ds_write_b64 v4, v[2:3]
	v_and_b32_e32 v2, -2, v66
	v_or_b32_e32 v4, 1, v66
	v_ashrrev_i32_e32 v3, 31, v2
	v_ashrrev_i32_e32 v5, 31, v4
	v_lshl_add_u64 v[58:59], s[4:5], 0, v[162:163]
	v_lshlrev_b64 v[2:3], 11, v[2:3]
	v_lshlrev_b64 v[4:5], 11, v[4:5]
	v_lshl_add_u64 v[2:3], v[58:59], 0, v[2:3]
	v_lshl_add_u64 v[6:7], v[58:59], 0, v[4:5]
	global_load_dwordx4 v[2:5], v[2:3], off
	s_nop 0
	global_load_dwordx4 v[6:9], v[6:7], off
	v_and_b32_e32 v10, -2, v67
	v_or_b32_e32 v12, 1, v67
	v_ashrrev_i32_e32 v11, 31, v10
	v_ashrrev_i32_e32 v13, 31, v12
	v_lshlrev_b64 v[10:11], 11, v[10:11]
	v_lshlrev_b64 v[12:13], 11, v[12:13]
	v_lshl_add_u64 v[10:11], v[58:59], 0, v[10:11]
	v_lshl_add_u64 v[14:15], v[58:59], 0, v[12:13]
	global_load_dwordx4 v[10:13], v[10:11], off
	s_nop 0
	global_load_dwordx4 v[14:17], v[14:15], off
	v_ashrrev_i32_e32 v68, 4, v69
	v_and_b32_e32 v18, -2, v68
	v_or_b32_e32 v20, 1, v68
	v_ashrrev_i32_e32 v19, 31, v18
	v_ashrrev_i32_e32 v21, 31, v20
	v_lshlrev_b64 v[18:19], 11, v[18:19]
	v_lshlrev_b64 v[20:21], 11, v[20:21]
	v_lshl_add_u64 v[18:19], v[58:59], 0, v[18:19]
	v_lshl_add_u64 v[22:23], v[58:59], 0, v[20:21]
	global_load_dwordx4 v[18:21], v[18:19], off
	s_nop 0
	global_load_dwordx4 v[22:25], v[22:23], off
	v_ashrrev_i32_e32 v69, 4, v71
	v_and_b32_e32 v26, -2, v69
	v_or_b32_e32 v28, 1, v69
	v_ashrrev_i32_e32 v27, 31, v26
	v_ashrrev_i32_e32 v29, 31, v28
	v_lshlrev_b64 v[26:27], 11, v[26:27]
	v_lshlrev_b64 v[28:29], 11, v[28:29]
	v_lshl_add_u64 v[26:27], v[58:59], 0, v[26:27]
	v_lshl_add_u64 v[30:31], v[58:59], 0, v[28:29]
	global_load_dwordx4 v[26:29], v[26:27], off
	s_nop 0
	global_load_dwordx4 v[30:33], v[30:31], off
	v_ashrrev_i32_e32 v70, 4, v73
	v_and_b32_e32 v34, -2, v70
	v_or_b32_e32 v36, 1, v70
	v_ashrrev_i32_e32 v35, 31, v34
	v_ashrrev_i32_e32 v37, 31, v36
	v_lshlrev_b64 v[34:35], 11, v[34:35]
	v_lshlrev_b64 v[36:37], 11, v[36:37]
	v_lshl_add_u64 v[34:35], v[58:59], 0, v[34:35]
	v_lshl_add_u64 v[38:39], v[58:59], 0, v[36:37]
	global_load_dwordx4 v[34:37], v[34:35], off
	s_nop 0
	global_load_dwordx4 v[38:41], v[38:39], off
	v_ashrrev_i32_e32 v71, 4, v75
	v_and_b32_e32 v42, -2, v71
	v_or_b32_e32 v44, 1, v71
	v_ashrrev_i32_e32 v43, 31, v42
	v_ashrrev_i32_e32 v45, 31, v44
	v_lshlrev_b64 v[42:43], 11, v[42:43]
	v_lshlrev_b64 v[44:45], 11, v[44:45]
	v_lshl_add_u64 v[42:43], v[58:59], 0, v[42:43]
	v_lshl_add_u64 v[46:47], v[58:59], 0, v[44:45]
	global_load_dwordx4 v[42:45], v[42:43], off
	s_nop 0
	global_load_dwordx4 v[46:49], v[46:47], off
	v_ashrrev_i32_e32 v72, 4, v77
	v_and_b32_e32 v50, -2, v72
	v_or_b32_e32 v52, 1, v72
	v_ashrrev_i32_e32 v51, 31, v50
	v_ashrrev_i32_e32 v53, 31, v52
	v_lshlrev_b64 v[50:51], 11, v[50:51]
	v_lshlrev_b64 v[52:53], 11, v[52:53]
	v_lshl_add_u64 v[50:51], v[58:59], 0, v[50:51]
	v_lshl_add_u64 v[54:55], v[58:59], 0, v[52:53]
	global_load_dwordx4 v[50:53], v[50:51], off
	s_nop 0
	global_load_dwordx4 v[54:57], v[54:55], off
	v_ashrrev_i32_e32 v73, 4, v79
	v_and_b32_e32 v60, -2, v73
	v_or_b32_e32 v62, 1, v73
	v_ashrrev_i32_e32 v61, 31, v60
	v_ashrrev_i32_e32 v63, 31, v62
	v_lshlrev_b64 v[60:61], 11, v[60:61]
	v_lshlrev_b64 v[62:63], 11, v[62:63]
	v_lshl_add_u64 v[60:61], v[58:59], 0, v[60:61]
	v_lshl_add_u64 v[62:63], v[58:59], 0, v[62:63]
	global_load_dwordx4 v[58:61], v[60:61], off
	s_nop 0
	global_load_dwordx4 v[62:65], v[62:63], off
	v_lshlrev_b32_e32 v75, 1, v66
	v_lshlrev_b32_e32 v74, 3, v160
	v_and_b32_e32 v76, 8, v75
	v_and_b32_e32 v77, 0x7ffffff0, v66
	v_bitop3_b32 v76, v76, v74, v77 bitop3:0x36
	v_lshlrev_b32_e32 v76, 1, v76
	v_and_b32_e32 v75, 4, v75
	v_add3_u32 v75, s37, v76, v75
	v_and_b32_e32 v66, 8, v66
	s_cselect_b64 s[4:5], -1, 0
	s_waitcnt vmcnt(14)
	v_cvt_pk_bf16_f32 v2, v2, v6
	v_mul_u32_u24_e32 v6, 0x840, v160
	v_add3_u32 v66, v75, v66, v6
	v_cvt_pk_bf16_f32 v3, v3, v7
	ds_write2_b32 v66, v2, v3 offset1:132
	v_cvt_pk_bf16_f32 v2, v4, v8
	v_cvt_pk_bf16_f32 v3, v5, v9
	v_add_u32_e32 v4, 0x400, v66
	ds_write2_b32 v4, v2, v3 offset0:8 offset1:140
	v_lshlrev_b32_e32 v2, 1, v67
	v_and_b32_e32 v3, 8, v2
	v_and_b32_e32 v4, 0x7ffffff0, v67
	v_bitop3_b32 v3, v3, v74, v4 bitop3:0x36
	v_lshlrev_b32_e32 v3, 1, v3
	v_and_b32_e32 v2, 4, v2
	v_add3_u32 v2, s37, v3, v2
	v_and_b32_e32 v3, 8, v67
	s_waitcnt vmcnt(12)
	v_cvt_pk_bf16_f32 v4, v10, v14
	v_add3_u32 v2, v2, v3, v6
	v_cvt_pk_bf16_f32 v3, v11, v15
	ds_write2_b32 v2, v4, v3 offset1:132
	v_cvt_pk_bf16_f32 v3, v12, v16
	v_cvt_pk_bf16_f32 v4, v13, v17
	v_add_u32_e32 v2, 0x400, v2
	ds_write2_b32 v2, v3, v4 offset0:8 offset1:140
	v_lshlrev_b32_e32 v2, 1, v68
	v_and_b32_e32 v3, 8, v2
	v_and_b32_e32 v4, 0x7ffffff0, v68
	v_bitop3_b32 v3, v3, v74, v4 bitop3:0x36
	v_lshlrev_b32_e32 v3, 1, v3
	v_and_b32_e32 v2, 4, v2
	v_add3_u32 v2, s37, v3, v2
	v_and_b32_e32 v3, 8, v68
	s_waitcnt vmcnt(10)
	v_cvt_pk_bf16_f32 v4, v18, v22
	v_add3_u32 v2, v2, v3, v6
	v_cvt_pk_bf16_f32 v3, v19, v23
	ds_write2_b32 v2, v4, v3 offset1:132
	v_cvt_pk_bf16_f32 v3, v20, v24
	v_cvt_pk_bf16_f32 v4, v21, v25
	v_add_u32_e32 v2, 0x400, v2
	ds_write2_b32 v2, v3, v4 offset0:8 offset1:140
	v_lshlrev_b32_e32 v2, 1, v69
	v_and_b32_e32 v3, 8, v2
	v_and_b32_e32 v4, 0x7ffffff0, v69
	v_bitop3_b32 v3, v3, v74, v4 bitop3:0x36
	v_lshlrev_b32_e32 v3, 1, v3
	v_and_b32_e32 v2, 4, v2
	v_add3_u32 v2, s37, v3, v2
	v_and_b32_e32 v3, 8, v69
	s_waitcnt vmcnt(8)
	v_cvt_pk_bf16_f32 v4, v26, v30
	v_add3_u32 v2, v2, v3, v6
	v_cvt_pk_bf16_f32 v3, v27, v31
	ds_write2_b32 v2, v4, v3 offset1:132
	v_cvt_pk_bf16_f32 v3, v28, v32
	v_cvt_pk_bf16_f32 v4, v29, v33
	v_add_u32_e32 v2, 0x400, v2
	ds_write2_b32 v2, v3, v4 offset0:8 offset1:140
	v_lshlrev_b32_e32 v2, 1, v70
	v_and_b32_e32 v3, 8, v2
	v_and_b32_e32 v4, 0x7ffffff0, v70
	v_bitop3_b32 v3, v3, v74, v4 bitop3:0x36
	v_lshlrev_b32_e32 v3, 1, v3
	v_and_b32_e32 v2, 4, v2
	v_add3_u32 v2, s37, v3, v2
	v_and_b32_e32 v3, 8, v70
	s_waitcnt vmcnt(6)
	v_cvt_pk_bf16_f32 v4, v34, v38
	v_add3_u32 v2, v2, v3, v6
	v_cvt_pk_bf16_f32 v3, v35, v39
	ds_write2_b32 v2, v4, v3 offset1:132
	v_cvt_pk_bf16_f32 v3, v36, v40
	v_cvt_pk_bf16_f32 v4, v37, v41
	v_add_u32_e32 v2, 0x400, v2
	ds_write2_b32 v2, v3, v4 offset0:8 offset1:140
	v_lshlrev_b32_e32 v2, 1, v71
	v_and_b32_e32 v3, 8, v2
	v_and_b32_e32 v4, 0x7ffffff0, v71
	v_bitop3_b32 v3, v3, v74, v4 bitop3:0x36
	v_lshlrev_b32_e32 v3, 1, v3
	v_and_b32_e32 v2, 4, v2
	v_add3_u32 v2, s37, v3, v2
	v_and_b32_e32 v3, 8, v71
	s_waitcnt vmcnt(4)
	v_cvt_pk_bf16_f32 v4, v42, v46
	v_add3_u32 v2, v2, v3, v6
	v_cvt_pk_bf16_f32 v3, v43, v47
	ds_write2_b32 v2, v4, v3 offset1:132
	v_cvt_pk_bf16_f32 v3, v44, v48
	v_cvt_pk_bf16_f32 v4, v45, v49
	v_add_u32_e32 v2, 0x400, v2
	ds_write2_b32 v2, v3, v4 offset0:8 offset1:140
	v_lshlrev_b32_e32 v2, 1, v72
	v_and_b32_e32 v3, 8, v2
	v_and_b32_e32 v4, 0x7ffffff0, v72
	v_bitop3_b32 v3, v3, v74, v4 bitop3:0x36
	v_lshlrev_b32_e32 v3, 1, v3
	v_and_b32_e32 v2, 4, v2
	v_add3_u32 v2, s37, v3, v2
	v_and_b32_e32 v3, 8, v72
	s_waitcnt vmcnt(2)
	v_cvt_pk_bf16_f32 v4, v50, v54
	v_add3_u32 v2, v2, v3, v6
	v_cvt_pk_bf16_f32 v3, v51, v55
	ds_write2_b32 v2, v4, v3 offset1:132
	v_cvt_pk_bf16_f32 v3, v52, v56
	v_cvt_pk_bf16_f32 v4, v53, v57
	v_add_u32_e32 v2, 0x400, v2
	ds_write2_b32 v2, v3, v4 offset0:8 offset1:140
	v_lshlrev_b32_e32 v2, 1, v73
	v_and_b32_e32 v3, 8, v2
	v_and_b32_e32 v4, 0x7ffffff0, v73
	v_bitop3_b32 v3, v3, v74, v4 bitop3:0x36
	v_lshlrev_b32_e32 v3, 1, v3
	v_and_b32_e32 v2, 4, v2
	v_add3_u32 v2, s37, v3, v2
	v_and_b32_e32 v3, 8, v73
	s_waitcnt vmcnt(0)
	v_cvt_pk_bf16_f32 v4, v58, v62
	v_add3_u32 v2, v2, v3, v6
	v_cvt_pk_bf16_f32 v3, v59, v63
	ds_write2_b32 v2, v4, v3 offset1:132
	v_cvt_pk_bf16_f32 v3, v60, v64
	v_cvt_pk_bf16_f32 v4, v61, v65
	v_add_u32_e32 v2, 0x400, v2
	ds_write2_b32 v2, v3, v4 offset0:8 offset1:140
	v_mov_b32_e32 v2, 0
	s_cmpk_gt_u32 s15, 0x1ff
	s_waitcnt lgkmcnt(0)
	s_barrier
	s_cbranch_scc1 .LBB0_1212
	s_lshl_b64 s[16:17], s[0:1], 10
	s_add_u32 s15, s41, s16
	s_addc_u32 s17, s42, s17
	s_lshl_b32 s16, s7, 1
	s_add_u32 s16, s15, s16
	v_or_b32_e32 v2, s6, v160
	s_addc_u32 s17, s17, 0
	v_lshlrev_b32_e32 v162, 10, v2
	v_lshl_add_u64 v[2:3], s[16:17], 0, v[162:163]
	v_mov_b32_e32 v159, v163
	v_lshl_add_u64 v[2:3], v[2:3], 0, v[158:159]
	v_mov_b32_e32 v50, v100
	v_mov_b32_e32 v51, v101
	v_mov_b32_e32 v52, v102
	v_mov_b32_e32 v53, v103
	s_nop 0
	s_nop 0
	s_nop 0
	s_nop 0
	s_nop 0
	s_nop 0
	s_nop 0
	v_mul_u32_u24_e32 v2, 0x110, v160
	v_add3_u32 v159, 0, v158, v2
	ds_read_b128 v[2:5], v159
	ds_read_b128 v[18:21], v159 offset:32
	s_mov_b32 s15, 0xff61b1e6
	s_waitcnt vmcnt(7) lgkmcnt(1)
	v_mfma_f32_32x32x16_bf16 v[2:17], v[2:5], v[50:53], 0
	s_waitcnt vmcnt(6) lgkmcnt(0)
	v_mfma_f32_32x32x16_bf16 v[2:17], v[18:21], v[154:157], v[2:17]
	ds_read_b128 v[18:21], v159 offset:64
	s_waitcnt vmcnt(5) lgkmcnt(0)
	v_mfma_f32_32x32x16_bf16 v[2:17], v[18:21], v[150:153], v[2:17]
	ds_read_b128 v[18:21], v159 offset:96
	s_waitcnt vmcnt(4) lgkmcnt(0)
	v_mfma_f32_32x32x16_bf16 v[2:17], v[18:21], v[146:149], v[2:17]
	ds_read_b128 v[18:21], v159 offset:128
	s_waitcnt vmcnt(3) lgkmcnt(0)
	v_mfma_f32_32x32x16_bf16 v[2:17], v[18:21], v[142:145], v[2:17]
	ds_read_b128 v[18:21], v159 offset:160
	s_waitcnt vmcnt(2) lgkmcnt(0)
	v_mfma_f32_32x32x16_bf16 v[2:17], v[18:21], v[138:141], v[2:17]
	ds_read_b128 v[18:21], v159 offset:192
	s_waitcnt vmcnt(1) lgkmcnt(0)
	v_mfma_f32_32x32x16_bf16 v[2:17], v[18:21], v[134:137], v[2:17]
	ds_read_b128 v[18:21], v159 offset:224
	s_waitcnt vmcnt(0) lgkmcnt(0)
	v_mfma_f32_32x32x16_bf16 v[2:17], v[18:21], v[130:133], v[2:17]
	ds_read_b128 v[18:21], v159 offset:8704
	ds_read_b128 v[34:37], v159 offset:8736
	s_waitcnt lgkmcnt(1)
	v_mfma_f32_32x32x16_bf16 v[18:33], v[18:21], v[50:53], 0
	s_waitcnt lgkmcnt(0)
	v_mfma_f32_32x32x16_bf16 v[18:33], v[34:37], v[154:157], v[18:33]
	ds_read_b128 v[34:37], v159 offset:8768
	s_waitcnt lgkmcnt(0)
	v_mfma_f32_32x32x16_bf16 v[18:33], v[34:37], v[150:153], v[18:33]
	ds_read_b128 v[34:37], v159 offset:8800
	s_waitcnt lgkmcnt(0)
	v_mfma_f32_32x32x16_bf16 v[18:33], v[34:37], v[146:149], v[18:33]
	ds_read_b128 v[34:37], v159 offset:8832
	s_waitcnt lgkmcnt(0)
	v_mfma_f32_32x32x16_bf16 v[18:33], v[34:37], v[142:145], v[18:33]
	ds_read_b128 v[34:37], v159 offset:8864
	s_waitcnt lgkmcnt(0)
	v_mfma_f32_32x32x16_bf16 v[18:33], v[34:37], v[138:141], v[18:33]
	ds_read_b128 v[34:37], v159 offset:8896
	s_waitcnt lgkmcnt(0)
	v_mfma_f32_32x32x16_bf16 v[18:33], v[34:37], v[134:137], v[18:33]
	ds_read_b128 v[34:37], v159 offset:8928
	s_waitcnt lgkmcnt(0)
	v_mfma_f32_32x32x16_bf16 v[18:33], v[34:37], v[130:133], v[18:33]
	ds_read_b128 v[34:37], v159 offset:17408
	ds_read_b128 v[54:57], v159 offset:17440
	s_waitcnt lgkmcnt(1)
	v_mfma_f32_32x32x16_bf16 v[34:49], v[34:37], v[50:53], 0
	s_waitcnt lgkmcnt(0)
	v_mfma_f32_32x32x16_bf16 v[34:49], v[54:57], v[154:157], v[34:49]
	ds_read_b128 v[54:57], v159 offset:17472
	s_waitcnt lgkmcnt(0)
	v_mfma_f32_32x32x16_bf16 v[34:49], v[54:57], v[150:153], v[34:49]
	ds_read_b128 v[54:57], v159 offset:17504
	s_waitcnt lgkmcnt(0)
	v_mfma_f32_32x32x16_bf16 v[34:49], v[54:57], v[146:149], v[34:49]
	ds_read_b128 v[54:57], v159 offset:17536
	s_waitcnt lgkmcnt(0)
	v_mfma_f32_32x32x16_bf16 v[34:49], v[54:57], v[142:145], v[34:49]
	ds_read_b128 v[54:57], v159 offset:17568
	s_waitcnt lgkmcnt(0)
	v_mfma_f32_32x32x16_bf16 v[34:49], v[54:57], v[138:141], v[34:49]
	ds_read_b128 v[54:57], v159 offset:17600
	s_waitcnt lgkmcnt(0)
	v_mfma_f32_32x32x16_bf16 v[34:49], v[54:57], v[134:137], v[34:49]
	ds_read_b128 v[54:57], v159 offset:17632
	s_waitcnt lgkmcnt(0)
	v_mfma_f32_32x32x16_bf16 v[34:49], v[54:57], v[130:133], v[34:49]
	ds_read_b128 v[54:57], v159 offset:26112
	ds_read_b128 v[58:61], v159 offset:26144
	s_waitcnt lgkmcnt(1)
	v_mfma_f32_32x32x16_bf16 v[114:129], v[54:57], v[50:53], 0
	ds_read_b128 v[54:57], v159 offset:26176
	s_waitcnt lgkmcnt(1)
	v_mfma_f32_32x32x16_bf16 v[114:129], v[58:61], v[154:157], v[114:129]
	s_waitcnt lgkmcnt(0)
	v_mfma_f32_32x32x16_bf16 v[114:129], v[54:57], v[150:153], v[114:129]
	ds_read_b128 v[54:57], v159 offset:26208
	s_waitcnt lgkmcnt(0)
	v_mfma_f32_32x32x16_bf16 v[114:129], v[54:57], v[146:149], v[114:129]
	ds_read_b128 v[54:57], v159 offset:26240
	s_waitcnt lgkmcnt(0)
	v_mfma_f32_32x32x16_bf16 v[114:129], v[54:57], v[142:145], v[114:129]
	ds_read_b128 v[54:57], v159 offset:26272
	s_waitcnt lgkmcnt(0)
	v_mfma_f32_32x32x16_bf16 v[114:129], v[54:57], v[138:141], v[114:129]
	ds_read_b128 v[54:57], v159 offset:26304
	s_waitcnt lgkmcnt(0)
	v_mfma_f32_32x32x16_bf16 v[114:129], v[54:57], v[134:137], v[114:129]
	ds_read_b128 v[54:57], v159 offset:26336
	s_waitcnt lgkmcnt(0)
	v_mfma_f32_32x32x16_bf16 v[114:129], v[54:57], v[130:133], v[114:129]
	ds_read_b128 v[54:57], v159 offset:34816
	ds_read_b128 v[58:61], v159 offset:34848
	s_waitcnt lgkmcnt(1)
	v_mfma_f32_32x32x16_bf16 v[98:113], v[54:57], v[50:53], 0
	ds_read_b128 v[54:57], v159 offset:34880
	s_waitcnt lgkmcnt(1)
	v_mfma_f32_32x32x16_bf16 v[98:113], v[58:61], v[154:157], v[98:113]
	s_waitcnt lgkmcnt(0)
	v_mfma_f32_32x32x16_bf16 v[98:113], v[54:57], v[150:153], v[98:113]
	ds_read_b128 v[54:57], v159 offset:34912
	s_waitcnt lgkmcnt(0)
	v_mfma_f32_32x32x16_bf16 v[98:113], v[54:57], v[146:149], v[98:113]
	ds_read_b128 v[54:57], v159 offset:34944
	s_waitcnt lgkmcnt(0)
	v_mfma_f32_32x32x16_bf16 v[98:113], v[54:57], v[142:145], v[98:113]
	ds_read_b128 v[54:57], v159 offset:34976
	s_waitcnt lgkmcnt(0)
	v_mfma_f32_32x32x16_bf16 v[98:113], v[54:57], v[138:141], v[98:113]
	ds_read_b128 v[54:57], v159 offset:35008
	s_waitcnt lgkmcnt(0)
	v_mfma_f32_32x32x16_bf16 v[98:113], v[54:57], v[134:137], v[98:113]
	ds_read_b128 v[54:57], v159 offset:35040
	s_waitcnt lgkmcnt(0)
	v_mfma_f32_32x32x16_bf16 v[98:113], v[54:57], v[130:133], v[98:113]
	ds_read_b128 v[54:57], v159 offset:43520
	ds_read_b128 v[58:61], v159 offset:43552
	s_waitcnt lgkmcnt(1)
	v_mfma_f32_32x32x16_bf16 v[82:97], v[54:57], v[50:53], 0
	ds_read_b128 v[54:57], v159 offset:43584
	s_waitcnt lgkmcnt(1)
	v_mfma_f32_32x32x16_bf16 v[82:97], v[58:61], v[154:157], v[82:97]
	s_waitcnt lgkmcnt(0)
	v_mfma_f32_32x32x16_bf16 v[82:97], v[54:57], v[150:153], v[82:97]
	ds_read_b128 v[54:57], v159 offset:43616
	s_waitcnt lgkmcnt(0)
	v_mfma_f32_32x32x16_bf16 v[82:97], v[54:57], v[146:149], v[82:97]
	ds_read_b128 v[54:57], v159 offset:43648
	s_waitcnt lgkmcnt(0)
	v_mfma_f32_32x32x16_bf16 v[82:97], v[54:57], v[142:145], v[82:97]
	ds_read_b128 v[54:57], v159 offset:43680
	s_waitcnt lgkmcnt(0)
	v_mfma_f32_32x32x16_bf16 v[82:97], v[54:57], v[138:141], v[82:97]
	ds_read_b128 v[54:57], v159 offset:43712
	s_waitcnt lgkmcnt(0)
	v_mfma_f32_32x32x16_bf16 v[82:97], v[54:57], v[134:137], v[82:97]
	ds_read_b128 v[54:57], v159 offset:43744
	s_waitcnt lgkmcnt(0)
	v_mfma_f32_32x32x16_bf16 v[82:97], v[54:57], v[130:133], v[82:97]
	ds_read_b128 v[54:57], v159 offset:52224
	ds_read_b128 v[58:61], v159 offset:52256
	s_waitcnt lgkmcnt(1)
	v_mfma_f32_32x32x16_bf16 v[66:81], v[54:57], v[50:53], 0
	ds_read_b128 v[54:57], v159 offset:52288
	s_waitcnt lgkmcnt(1)
	v_mfma_f32_32x32x16_bf16 v[66:81], v[58:61], v[154:157], v[66:81]
	s_waitcnt lgkmcnt(0)
	v_mfma_f32_32x32x16_bf16 v[66:81], v[54:57], v[150:153], v[66:81]
	ds_read_b128 v[54:57], v159 offset:52320
	s_waitcnt lgkmcnt(0)
	v_mfma_f32_32x32x16_bf16 v[66:81], v[54:57], v[146:149], v[66:81]
	ds_read_b128 v[54:57], v159 offset:52352
	s_waitcnt lgkmcnt(0)
	v_mfma_f32_32x32x16_bf16 v[66:81], v[54:57], v[142:145], v[66:81]
	ds_read_b128 v[54:57], v159 offset:52384
	s_waitcnt lgkmcnt(0)
	v_mfma_f32_32x32x16_bf16 v[66:81], v[54:57], v[138:141], v[66:81]
	ds_read_b128 v[54:57], v159 offset:52416
	s_waitcnt lgkmcnt(0)
	v_mfma_f32_32x32x16_bf16 v[66:81], v[54:57], v[134:137], v[66:81]
	ds_read_b128 v[54:57], v159 offset:52448
	s_waitcnt lgkmcnt(0)
	v_mfma_f32_32x32x16_bf16 v[66:81], v[54:57], v[130:133], v[66:81]
	ds_read_b128 v[54:57], v159 offset:60928
	ds_read_b128 v[174:177], v159 offset:60960
	s_waitcnt lgkmcnt(1)
	v_mfma_f32_32x32x16_bf16 v[50:65], v[54:57], v[50:53], 0
	s_waitcnt lgkmcnt(0)
	v_mfma_f32_32x32x16_bf16 v[50:65], v[174:177], v[154:157], v[50:65]
	ds_read_b128 v[154:157], v159 offset:60992
	s_waitcnt lgkmcnt(0)
	v_mfma_f32_32x32x16_bf16 v[50:65], v[154:157], v[150:153], v[50:65]
	ds_read_b128 v[150:153], v159 offset:61024
	s_waitcnt lgkmcnt(0)
	v_mfma_f32_32x32x16_bf16 v[50:65], v[150:153], v[146:149], v[50:65]
	ds_read_b128 v[146:149], v159 offset:61056
	s_waitcnt lgkmcnt(0)
	v_mfma_f32_32x32x16_bf16 v[50:65], v[146:149], v[142:145], v[50:65]
	ds_read_b128 v[142:145], v159 offset:61088
	s_waitcnt lgkmcnt(0)
	v_mfma_f32_32x32x16_bf16 v[50:65], v[142:145], v[138:141], v[50:65]
	ds_read_b128 v[138:141], v159 offset:61120
	s_waitcnt lgkmcnt(0)
	v_mfma_f32_32x32x16_bf16 v[50:65], v[138:141], v[134:137], v[50:65]
	ds_read_b128 v[134:137], v159 offset:61152
	s_waitcnt lgkmcnt(0)
	v_mfma_f32_32x32x16_bf16 v[50:65], v[134:137], v[130:133], v[50:65]
	v_max3_f32 v130, v2, s15, v3
	v_max3_f32 v130, v130, v4, v5
	v_max3_f32 v130, v130, v6, v7
	v_max3_f32 v130, v130, v8, v9
	v_max3_f32 v130, v130, v10, v11
	v_max3_f32 v130, v130, v12, v13
	v_max3_f32 v130, v130, v14, v15
	v_max3_f32 v130, v130, v16, v17
	v_max3_f32 v130, v130, v18, v19
	v_max3_f32 v130, v130, v20, v21
	v_max3_f32 v130, v130, v22, v23
	v_max3_f32 v130, v130, v24, v25
	v_max3_f32 v130, v130, v26, v27
	v_max3_f32 v130, v130, v28, v29
	v_max3_f32 v130, v130, v30, v31
	v_max3_f32 v130, v130, v32, v33
	v_max3_f32 v130, v130, v34, v35
	v_max3_f32 v130, v130, v36, v37
	v_max3_f32 v130, v130, v38, v39
	v_max3_f32 v130, v130, v40, v41
	v_max3_f32 v130, v130, v42, v43
	v_max3_f32 v130, v130, v44, v45
	v_max3_f32 v130, v130, v46, v47
	v_max3_f32 v130, v130, v48, v49
	v_max3_f32 v130, v130, v114, v115
	v_max3_f32 v130, v130, v116, v117
	v_max3_f32 v130, v130, v118, v119
	v_max3_f32 v130, v130, v120, v121
	v_max3_f32 v130, v130, v122, v123
	v_max3_f32 v130, v130, v124, v125
	v_max3_f32 v130, v130, v126, v127
	v_max3_f32 v130, v130, v128, v129
	v_max3_f32 v130, v130, v98, v99
	v_max3_f32 v130, v130, v100, v101
	v_max3_f32 v130, v130, v102, v103
	v_max3_f32 v130, v130, v104, v105
	v_max3_f32 v130, v130, v106, v107
	v_max3_f32 v130, v130, v108, v109
	v_max3_f32 v130, v130, v110, v111
	v_max3_f32 v130, v130, v112, v113
	v_max3_f32 v130, v130, v82, v83
	v_max3_f32 v130, v130, v84, v85
	v_max3_f32 v130, v130, v86, v87
	v_max3_f32 v130, v130, v88, v89
	v_max3_f32 v130, v130, v90, v91
	v_max3_f32 v130, v130, v92, v93
	v_max3_f32 v130, v130, v94, v95
	v_max3_f32 v130, v130, v96, v97
	v_max3_f32 v130, v130, v66, v67
	v_max3_f32 v130, v130, v68, v69
	v_max3_f32 v130, v130, v70, v71
	v_max3_f32 v130, v130, v72, v73
	v_max3_f32 v130, v130, v74, v75
	v_max3_f32 v130, v130, v76, v77
	v_max3_f32 v130, v130, v78, v79
	v_max3_f32 v130, v130, v80, v81
	v_max3_f32 v130, v130, v50, v51
	v_max3_f32 v130, v130, v52, v53
	v_max3_f32 v130, v130, v54, v55
	v_max3_f32 v130, v130, v56, v57
	v_and_b32_e32 v132, 64, v1
	v_max3_f32 v130, v130, v58, v59
	v_xor_b32_e32 v131, 32, v1
	v_add_u32_e32 v132, 64, v132
	v_max3_f32 v130, v130, v60, v61
	v_cmp_lt_i32_e32 vcc, v131, v132
	v_max3_f32 v130, v130, v62, v63
	v_max3_f32 v130, v130, v64, v65
	v_cndmask_b32_e32 v131, v1, v131, vcc
	v_lshlrev_b32_e32 v146, 2, v131
	ds_bpermute_b32 v131, v146, v130
	s_waitcnt lgkmcnt(0)
	v_max_f32_e32 v131, v131, v131
	v_max_f32_e32 v147, v130, v131
	v_sub_f32_e32 v2, v2, v147
	v_sub_f32_e32 v3, v3, v147
	v_exp_f32_e32 v2, v2
	v_exp_f32_e32 v3, v3
	v_sub_f32_e32 v4, v4, v147
	v_exp_f32_e32 v4, v4
	v_sub_f32_e32 v5, v5, v147
	v_exp_f32_e32 v5, v5
	v_sub_f32_e32 v6, v6, v147
	v_exp_f32_e32 v6, v6
	v_sub_f32_e32 v7, v7, v147
	v_cvt_pk_bf16_f32 v134, v2, v3
	v_add_f32_e32 v2, 0, v2
	v_exp_f32_e32 v7, v7
	v_sub_f32_e32 v8, v8, v147
	v_add_f32_e32 v2, v3, v2
	v_exp_f32_e32 v8, v8
	v_sub_f32_e32 v9, v9, v147
	v_add_f32_e32 v2, v4, v2
	v_exp_f32_e32 v9, v9
	v_sub_f32_e32 v10, v10, v147
	v_add_f32_e32 v2, v5, v2
	v_exp_f32_e32 v10, v10
	v_sub_f32_e32 v11, v11, v147
	v_add_f32_e32 v2, v6, v2
	v_exp_f32_e32 v11, v11
	v_sub_f32_e32 v12, v12, v147
	v_add_f32_e32 v2, v7, v2
	v_exp_f32_e32 v12, v12
	v_sub_f32_e32 v13, v13, v147
	v_add_f32_e32 v2, v8, v2
	v_exp_f32_e32 v13, v13
	v_sub_f32_e32 v14, v14, v147
	v_add_f32_e32 v2, v9, v2
	v_exp_f32_e32 v14, v14
	v_sub_f32_e32 v15, v15, v147
	v_add_f32_e32 v2, v10, v2
	v_exp_f32_e32 v15, v15
	v_sub_f32_e32 v16, v16, v147
	v_add_f32_e32 v2, v11, v2
	v_exp_f32_e32 v16, v16
	v_sub_f32_e32 v17, v17, v147
	v_add_f32_e32 v2, v12, v2
	v_exp_f32_e32 v17, v17
	v_add_f32_e32 v2, v13, v2
	v_sub_f32_e32 v3, v18, v147
	v_cvt_pk_bf16_f32 v135, v4, v5
	v_add_f32_e32 v2, v14, v2
	v_exp_f32_e32 v3, v3
	v_sub_f32_e32 v4, v19, v147
	v_add_f32_e32 v2, v15, v2
	v_exp_f32_e32 v4, v4
	v_sub_f32_e32 v5, v20, v147
	v_cvt_pk_bf16_f32 v136, v6, v7
	v_add_f32_e32 v2, v16, v2
	v_exp_f32_e32 v5, v5
	v_sub_f32_e32 v6, v21, v147
	v_add_f32_e32 v2, v17, v2
	v_exp_f32_e32 v6, v6
	v_sub_f32_e32 v7, v22, v147
	v_cvt_pk_bf16_f32 v137, v8, v9
	v_exp_f32_e32 v7, v7
	v_sub_f32_e32 v8, v23, v147
	v_add_f32_e32 v2, v3, v2
	v_exp_f32_e32 v8, v8
	v_sub_f32_e32 v9, v24, v147
	v_add_f32_e32 v2, v4, v2
	v_cvt_pk_bf16_f32 v130, v10, v11
	v_exp_f32_e32 v9, v9
	v_sub_f32_e32 v10, v25, v147
	v_add_f32_e32 v2, v5, v2
	v_exp_f32_e32 v10, v10
	v_sub_f32_e32 v11, v26, v147
	v_add_f32_e32 v2, v6, v2
	v_cvt_pk_bf16_f32 v131, v12, v13
	v_exp_f32_e32 v11, v11
	v_sub_f32_e32 v12, v27, v147
	v_add_f32_e32 v2, v7, v2
	v_exp_f32_e32 v12, v12
	v_sub_f32_e32 v13, v28, v147
	v_add_f32_e32 v2, v8, v2
	v_cvt_pk_bf16_f32 v132, v14, v15
	v_exp_f32_e32 v13, v13
	v_sub_f32_e32 v14, v29, v147
	v_add_f32_e32 v2, v9, v2
	v_exp_f32_e32 v14, v14
	v_sub_f32_e32 v15, v30, v147
	v_add_f32_e32 v2, v10, v2
	v_cvt_pk_bf16_f32 v133, v16, v17
	v_exp_f32_e32 v15, v15
	v_sub_f32_e32 v16, v31, v147
	v_add_f32_e32 v2, v11, v2
	v_exp_f32_e32 v16, v16
	v_sub_f32_e32 v17, v32, v147
	v_add_f32_e32 v2, v12, v2
	v_exp_f32_e32 v17, v17
	v_sub_f32_e32 v18, v33, v147
	v_add_f32_e32 v2, v13, v2
	v_exp_f32_e32 v18, v18
	v_cvt_pk_bf16_f32 v142, v3, v4
	v_add_f32_e32 v2, v14, v2
	v_sub_f32_e32 v3, v34, v147
	v_add_f32_e32 v2, v15, v2
	v_exp_f32_e32 v3, v3
	v_sub_f32_e32 v4, v35, v147
	v_cvt_pk_bf16_f32 v143, v5, v6
	v_add_f32_e32 v2, v16, v2
	v_exp_f32_e32 v4, v4
	v_sub_f32_e32 v5, v36, v147
	v_add_f32_e32 v2, v17, v2
	v_exp_f32_e32 v5, v5
	v_sub_f32_e32 v6, v37, v147
	v_cvt_pk_bf16_f32 v144, v7, v8
	v_add_f32_e32 v2, v18, v2
	v_exp_f32_e32 v6, v6
	v_sub_f32_e32 v7, v38, v147
	v_exp_f32_e32 v7, v7
	v_sub_f32_e32 v8, v39, v147
	v_add_f32_e32 v2, v3, v2
	v_cvt_pk_bf16_f32 v145, v9, v10
	v_exp_f32_e32 v8, v8
	v_sub_f32_e32 v9, v40, v147
	v_add_f32_e32 v2, v4, v2
	v_exp_f32_e32 v9, v9
	v_sub_f32_e32 v10, v41, v147
	v_add_f32_e32 v2, v5, v2
	v_cvt_pk_bf16_f32 v138, v11, v12
	v_exp_f32_e32 v10, v10
	v_sub_f32_e32 v11, v42, v147
	v_add_f32_e32 v2, v6, v2
	v_exp_f32_e32 v11, v11
	v_sub_f32_e32 v12, v43, v147
	v_add_f32_e32 v2, v7, v2
	v_cvt_pk_bf16_f32 v139, v13, v14
	v_exp_f32_e32 v12, v12
	v_sub_f32_e32 v13, v44, v147
	v_add_f32_e32 v2, v8, v2
	v_exp_f32_e32 v13, v13
	v_sub_f32_e32 v14, v45, v147
	v_add_f32_e32 v2, v9, v2
	v_cvt_pk_bf16_f32 v140, v15, v16
	v_exp_f32_e32 v14, v14
	v_sub_f32_e32 v15, v46, v147
	v_add_f32_e32 v2, v10, v2
	v_exp_f32_e32 v15, v15
	v_sub_f32_e32 v16, v47, v147
	v_add_f32_e32 v2, v11, v2
	v_cvt_pk_bf16_f32 v141, v17, v18
	v_exp_f32_e32 v16, v16
	v_sub_f32_e32 v17, v48, v147
	v_add_f32_e32 v2, v12, v2
	v_exp_f32_e32 v17, v17
	v_sub_f32_e32 v18, v49, v147
	v_add_f32_e32 v2, v13, v2
	v_exp_f32_e32 v18, v18
	v_cvt_pk_bf16_f32 v38, v3, v4
	v_add_f32_e32 v2, v14, v2
	v_sub_f32_e32 v3, v114, v147
	v_add_f32_e32 v2, v15, v2
	v_exp_f32_e32 v3, v3
	v_sub_f32_e32 v4, v115, v147
	v_cvt_pk_bf16_f32 v39, v5, v6
	v_add_f32_e32 v2, v16, v2
	v_exp_f32_e32 v4, v4
	v_sub_f32_e32 v5, v116, v147
	v_add_f32_e32 v2, v17, v2
	v_exp_f32_e32 v5, v5
	v_sub_f32_e32 v6, v117, v147
	v_cvt_pk_bf16_f32 v40, v7, v8
	v_add_f32_e32 v2, v18, v2
	v_exp_f32_e32 v6, v6
	v_sub_f32_e32 v7, v118, v147
	v_exp_f32_e32 v7, v7
	v_sub_f32_e32 v8, v119, v147
	v_add_f32_e32 v2, v3, v2
	v_cvt_pk_bf16_f32 v41, v9, v10
	v_exp_f32_e32 v8, v8
	v_sub_f32_e32 v9, v120, v147
	v_add_f32_e32 v2, v4, v2
	v_exp_f32_e32 v9, v9
	v_sub_f32_e32 v10, v121, v147
	v_add_f32_e32 v2, v5, v2
	v_cvt_pk_bf16_f32 v34, v11, v12
	v_exp_f32_e32 v10, v10
	v_sub_f32_e32 v11, v122, v147
	v_add_f32_e32 v2, v6, v2
	v_exp_f32_e32 v11, v11
	v_sub_f32_e32 v12, v123, v147
	v_add_f32_e32 v2, v7, v2
	v_cvt_pk_bf16_f32 v35, v13, v14
	v_exp_f32_e32 v12, v12
	v_sub_f32_e32 v13, v124, v147
	v_add_f32_e32 v2, v8, v2
	v_exp_f32_e32 v13, v13
	v_sub_f32_e32 v14, v125, v147
	v_add_f32_e32 v2, v9, v2
	v_cvt_pk_bf16_f32 v36, v15, v16
	v_exp_f32_e32 v14, v14
	v_sub_f32_e32 v15, v126, v147
	v_add_f32_e32 v2, v10, v2
	v_exp_f32_e32 v15, v15
	v_sub_f32_e32 v16, v127, v147
	v_add_f32_e32 v2, v11, v2
	v_cvt_pk_bf16_f32 v37, v17, v18
	v_exp_f32_e32 v16, v16
	v_sub_f32_e32 v17, v128, v147
	v_add_f32_e32 v2, v12, v2
	v_exp_f32_e32 v17, v17
	v_sub_f32_e32 v18, v129, v147
	v_add_f32_e32 v2, v13, v2
	v_exp_f32_e32 v18, v18
	v_cvt_pk_bf16_f32 v46, v3, v4
	v_add_f32_e32 v2, v14, v2
	v_sub_f32_e32 v3, v98, v147
	v_add_f32_e32 v2, v15, v2
	v_exp_f32_e32 v3, v3
	v_sub_f32_e32 v4, v99, v147
	v_cvt_pk_bf16_f32 v47, v5, v6
	v_add_f32_e32 v2, v16, v2
	v_exp_f32_e32 v4, v4
	v_sub_f32_e32 v5, v100, v147
	v_add_f32_e32 v2, v17, v2
	v_exp_f32_e32 v5, v5
	v_sub_f32_e32 v6, v101, v147
	v_cvt_pk_bf16_f32 v48, v7, v8
	v_add_f32_e32 v2, v18, v2
	v_exp_f32_e32 v6, v6
	v_sub_f32_e32 v7, v102, v147
	v_exp_f32_e32 v7, v7
	v_sub_f32_e32 v8, v103, v147
	v_add_f32_e32 v2, v3, v2
	v_cvt_pk_bf16_f32 v49, v9, v10
	v_exp_f32_e32 v8, v8
	v_sub_f32_e32 v9, v104, v147
	v_add_f32_e32 v2, v4, v2
	v_exp_f32_e32 v9, v9
	v_sub_f32_e32 v10, v105, v147
	v_add_f32_e32 v2, v5, v2
	v_cvt_pk_bf16_f32 v42, v11, v12
	v_exp_f32_e32 v10, v10
	v_sub_f32_e32 v11, v106, v147
	v_add_f32_e32 v2, v6, v2
	v_exp_f32_e32 v11, v11
	v_sub_f32_e32 v12, v107, v147
	v_add_f32_e32 v2, v7, v2
	v_cvt_pk_bf16_f32 v43, v13, v14
	v_exp_f32_e32 v12, v12
	v_sub_f32_e32 v13, v108, v147
	v_add_f32_e32 v2, v8, v2
	v_exp_f32_e32 v13, v13
	v_sub_f32_e32 v14, v109, v147
	v_add_f32_e32 v2, v9, v2
	v_cvt_pk_bf16_f32 v44, v15, v16
	v_exp_f32_e32 v14, v14
	v_sub_f32_e32 v15, v110, v147
	v_add_f32_e32 v2, v10, v2
	v_exp_f32_e32 v15, v15
	v_sub_f32_e32 v16, v111, v147
	v_add_f32_e32 v2, v11, v2
	v_cvt_pk_bf16_f32 v45, v17, v18
	v_exp_f32_e32 v16, v16
	v_sub_f32_e32 v17, v112, v147
	v_add_f32_e32 v2, v12, v2
	v_exp_f32_e32 v17, v17
	v_sub_f32_e32 v18, v113, v147
	v_add_f32_e32 v2, v13, v2
	v_exp_f32_e32 v18, v18
	v_cvt_pk_bf16_f32 v102, v3, v4
	v_add_f32_e32 v2, v14, v2
	v_sub_f32_e32 v3, v82, v147
	v_add_f32_e32 v2, v15, v2
	v_exp_f32_e32 v3, v3
	v_sub_f32_e32 v4, v83, v147
	v_cvt_pk_bf16_f32 v103, v5, v6
	v_add_f32_e32 v2, v16, v2
	v_exp_f32_e32 v4, v4
	v_sub_f32_e32 v5, v84, v147
	v_add_f32_e32 v2, v17, v2
	v_exp_f32_e32 v5, v5
	v_sub_f32_e32 v6, v85, v147
	v_cvt_pk_bf16_f32 v104, v7, v8
	v_add_f32_e32 v2, v18, v2
	v_exp_f32_e32 v6, v6
	v_sub_f32_e32 v7, v86, v147
	v_exp_f32_e32 v7, v7
	v_sub_f32_e32 v8, v87, v147
	v_add_f32_e32 v2, v3, v2
	v_cvt_pk_bf16_f32 v105, v9, v10
	v_exp_f32_e32 v8, v8
	v_sub_f32_e32 v9, v88, v147
	v_add_f32_e32 v2, v4, v2
	v_exp_f32_e32 v9, v9
	v_sub_f32_e32 v10, v89, v147
	v_add_f32_e32 v2, v5, v2
	v_cvt_pk_bf16_f32 v98, v11, v12
	v_exp_f32_e32 v10, v10
	v_sub_f32_e32 v11, v90, v147
	v_add_f32_e32 v2, v6, v2
	v_exp_f32_e32 v11, v11
	v_sub_f32_e32 v12, v91, v147
	v_add_f32_e32 v2, v7, v2
	v_cvt_pk_bf16_f32 v99, v13, v14
	v_exp_f32_e32 v12, v12
	v_sub_f32_e32 v13, v92, v147
	v_add_f32_e32 v2, v8, v2
	v_exp_f32_e32 v13, v13
	v_sub_f32_e32 v14, v93, v147
	v_add_f32_e32 v2, v9, v2
	v_cvt_pk_bf16_f32 v100, v15, v16
	v_exp_f32_e32 v14, v14
	v_sub_f32_e32 v15, v94, v147
	v_add_f32_e32 v2, v10, v2
	v_exp_f32_e32 v15, v15
	v_sub_f32_e32 v16, v95, v147
	v_add_f32_e32 v2, v11, v2
	v_cvt_pk_bf16_f32 v101, v17, v18
	v_exp_f32_e32 v16, v16
	v_sub_f32_e32 v17, v96, v147
	v_add_f32_e32 v2, v12, v2
	v_exp_f32_e32 v17, v17
	v_sub_f32_e32 v18, v97, v147
	v_add_f32_e32 v2, v13, v2
	v_exp_f32_e32 v18, v18
	v_cvt_pk_bf16_f32 v86, v3, v4
	v_add_f32_e32 v2, v14, v2
	v_sub_f32_e32 v3, v66, v147
	v_add_f32_e32 v2, v15, v2
	v_exp_f32_e32 v3, v3
	v_sub_f32_e32 v4, v67, v147
	v_cvt_pk_bf16_f32 v87, v5, v6
	v_add_f32_e32 v2, v16, v2
	v_exp_f32_e32 v4, v4
	v_sub_f32_e32 v5, v68, v147
	v_add_f32_e32 v2, v17, v2
	v_exp_f32_e32 v5, v5
	v_sub_f32_e32 v6, v69, v147
	v_cvt_pk_bf16_f32 v88, v7, v8
	v_add_f32_e32 v2, v18, v2
	v_exp_f32_e32 v6, v6
	v_sub_f32_e32 v7, v70, v147
	v_exp_f32_e32 v7, v7
	v_sub_f32_e32 v8, v71, v147
	v_add_f32_e32 v2, v3, v2
	v_cvt_pk_bf16_f32 v89, v9, v10
	v_exp_f32_e32 v8, v8
	v_sub_f32_e32 v9, v72, v147
	v_add_f32_e32 v2, v4, v2
	v_exp_f32_e32 v9, v9
	v_sub_f32_e32 v10, v73, v147
	v_add_f32_e32 v2, v5, v2
	v_cvt_pk_bf16_f32 v82, v11, v12
	v_exp_f32_e32 v10, v10
	v_sub_f32_e32 v11, v74, v147
	v_add_f32_e32 v2, v6, v2
	v_exp_f32_e32 v11, v11
	v_sub_f32_e32 v12, v75, v147
	v_add_f32_e32 v2, v7, v2
	v_cvt_pk_bf16_f32 v83, v13, v14
	v_exp_f32_e32 v12, v12
	v_sub_f32_e32 v13, v76, v147
	v_add_f32_e32 v2, v8, v2
	v_exp_f32_e32 v13, v13
	v_sub_f32_e32 v14, v77, v147
	v_add_f32_e32 v2, v9, v2
	v_cvt_pk_bf16_f32 v84, v15, v16
	v_exp_f32_e32 v14, v14
	v_sub_f32_e32 v15, v78, v147
	v_add_f32_e32 v2, v10, v2
	v_exp_f32_e32 v15, v15
	v_sub_f32_e32 v16, v79, v147
	v_add_f32_e32 v2, v11, v2
	v_cvt_pk_bf16_f32 v85, v17, v18
	v_exp_f32_e32 v16, v16
	v_sub_f32_e32 v17, v80, v147
	v_add_f32_e32 v2, v12, v2
	v_exp_f32_e32 v17, v17
	v_sub_f32_e32 v18, v81, v147
	v_add_f32_e32 v2, v13, v2
	v_exp_f32_e32 v18, v18
	v_cvt_pk_bf16_f32 v70, v3, v4
	v_add_f32_e32 v2, v14, v2
	v_sub_f32_e32 v3, v50, v147
	v_add_f32_e32 v2, v15, v2
	v_exp_f32_e32 v3, v3
	v_sub_f32_e32 v4, v51, v147
	v_cvt_pk_bf16_f32 v71, v5, v6
	v_add_f32_e32 v2, v16, v2
	v_exp_f32_e32 v4, v4
	v_sub_f32_e32 v5, v52, v147
	v_add_f32_e32 v2, v17, v2
	v_exp_f32_e32 v5, v5
	v_sub_f32_e32 v6, v53, v147
	v_cvt_pk_bf16_f32 v72, v7, v8
	v_add_f32_e32 v2, v18, v2
	v_exp_f32_e32 v6, v6
	v_sub_f32_e32 v7, v54, v147
	v_exp_f32_e32 v7, v7
	v_sub_f32_e32 v8, v55, v147
	v_add_f32_e32 v2, v3, v2
	v_cvt_pk_bf16_f32 v73, v9, v10
	v_exp_f32_e32 v8, v8
	v_sub_f32_e32 v9, v56, v147
	v_add_f32_e32 v2, v4, v2
	v_exp_f32_e32 v9, v9
	v_sub_f32_e32 v10, v57, v147
	v_add_f32_e32 v2, v5, v2
	v_cvt_pk_bf16_f32 v66, v11, v12
	v_exp_f32_e32 v10, v10
	v_sub_f32_e32 v11, v58, v147
	v_add_f32_e32 v2, v6, v2
	v_exp_f32_e32 v11, v11
	v_sub_f32_e32 v12, v59, v147
	v_add_f32_e32 v2, v7, v2
	v_cvt_pk_bf16_f32 v67, v13, v14
	v_exp_f32_e32 v12, v12
	v_sub_f32_e32 v13, v60, v147
	v_add_f32_e32 v2, v8, v2
	v_exp_f32_e32 v13, v13
	v_sub_f32_e32 v14, v61, v147
	v_add_f32_e32 v2, v9, v2
	v_cvt_pk_bf16_f32 v68, v15, v16
	v_exp_f32_e32 v14, v14
	v_sub_f32_e32 v15, v62, v147
	v_add_f32_e32 v2, v10, v2
	v_exp_f32_e32 v15, v15
	v_sub_f32_e32 v16, v63, v147
	v_add_f32_e32 v2, v11, v2
	v_cvt_pk_bf16_f32 v69, v17, v18
	v_exp_f32_e32 v16, v16
	v_sub_f32_e32 v17, v64, v147
	v_add_f32_e32 v2, v12, v2
	v_exp_f32_e32 v17, v17
	v_sub_f32_e32 v18, v65, v147
	v_add_f32_e32 v2, v13, v2
	v_exp_f32_e32 v18, v18
	v_add_f32_e32 v2, v14, v2
	v_add_f32_e32 v2, v15, v2
	v_add_f32_e32 v2, v16, v2
	v_add_f32_e32 v2, v17, v2
	v_add_f32_e32 v2, v18, v2
	v_cvt_pk_bf16_f32 v54, v3, v4
	ds_bpermute_b32 v3, v146, v2
	v_cvt_pk_bf16_f32 v55, v5, v6
	v_cvt_pk_bf16_f32 v56, v7, v8
	v_cvt_pk_bf16_f32 v57, v9, v10
	v_cvt_pk_bf16_f32 v50, v11, v12
	s_waitcnt lgkmcnt(0)
	v_add_f32_e32 v2, v2, v3
	v_div_scale_f32 v3, s[16:17], v2, v2, 1.0
	v_rcp_f32_e32 v4, v3
	v_cvt_pk_bf16_f32 v51, v13, v14
	v_cvt_pk_bf16_f32 v52, v15, v16
	v_cvt_pk_bf16_f32 v53, v17, v18
	v_fma_f32 v5, -v3, v4, 1.0
	v_fmac_f32_e32 v4, v5, v4
	v_div_scale_f32 v5, vcc, 1.0, v2, 1.0
	v_mul_f32_e32 v6, v5, v4
	v_fma_f32 v7, -v3, v6, v5
	v_fmac_f32_e32 v6, v7, v4
	v_fma_f32 v3, -v3, v6, v5
	v_div_fmas_f32 v3, v3, v4, v6
	v_div_fixup_f32 v2, v3, v2, 1.0
